# decode-row NSA compressed branch: bf16 row loads go straight to their destination group, one wait and unpack per batch
# speedup vs baseline: 1.0124x; 1.0005x over previous
; DI void snsa_unit(const Args& a, LAS unsigned char* lds, int s, int g) {
;     ...
;             for (int u = 0; u < 8; ++u) { const int kk = k0 + 32 * u; const int kc = kk < nkeys ? kk : k0;
;                 if (br == 0) { const u32x2 w = *(const u32x2*)(kcb + (size_t)kc * 64 + 4 * c16); x[u] = (f32x4){bf2f(w.x & 0xffffu), bf2f(w.x >> 16), bf2f(w.y & 0xffffu), bf2f(w.y >> 16)}; dist[u] = 16353 - 16 * kc; valid[u] = true; }
.LBB0_1475:
	s_waitcnt lgkmcnt(0)
	v_mov_b64_e32 v[20:21], v[10:11]
	v_mov_b64_e32 v[18:19], v[8:9]
	v_mov_b64_e32 v[16:17], v[6:7]
	v_mov_b64_e32 v[14:15], v[4:5]
	s_cbranch_execz .LBB0_1477
	global_load_dwordx2 v[38:39], v[90:91], off
	s_or_b64 s[20:21], s[20:21], exec

; DI void snsa_unit(const Args& a, LAS unsigned char* lds, int s, int g) {
;     ...
;             for (int u = 0; u < 8; ++u) { const int kk = k0 + 32 * u; const int kc = kk < nkeys ? kk : k0;
;                 if (br == 0) { const u32x2 w = *(const u32x2*)(kcb + (size_t)kc * 64 + 4 * c16); x[u] = (f32x4){bf2f(w.x & 0xffffu), bf2f(w.x >> 16), bf2f(w.y & 0xffffu), bf2f(w.y >> 16)}; dist[u] = 16353 - 16 * kc; valid[u] = true; }
.LBB0_1487:
	s_and_b64 vcc, exec, s[4:5]
	s_cbranch_vccz .LBB0_1489
	v_ashrrev_i32_e32 v47, 31, v46
	v_lshlrev_b64 v[6:7], 7, v[46:47]
	v_lshl_add_u64 v[6:7], v[78:79], 0, v[6:7]
	global_load_dwordx2 v[42:43], v[6:7], off
	v_lshlrev_b32_e32 v8, 4, v46
	s_waitcnt lgkmcnt(0)
	v_sub_u32_e32 v15, 0x3fe1, v8
	s_andn2_b64 s[4:5], s[20:21], exec
	s_and_b64 s[20:21], s[20:21], exec
	s_or_b64 s[58:59], s[58:59], exec
	s_or_b64 s[20:21], s[4:5], s[20:21]
	v_mov_b64_e32 v[6:7], v[14:15]
	v_mov_b64_e32 v[8:9], v[16:17]
	v_mov_b64_e32 v[10:11], v[18:19]
	v_mov_b64_e32 v[12:13], v[20:21]

; DI void snsa_unit(const Args& a, LAS unsigned char* lds, int s, int g) {
;     ...
;             for (int u = 0; u < 8; ++u) { const int kk = k0 + 32 * u; const int kc = kk < nkeys ? kk : k0;
;                 if (br == 0) { const u32x2 w = *(const u32x2*)(kcb + (size_t)kc * 64 + 4 * c16); x[u] = (f32x4){bf2f(w.x & 0xffffu), bf2f(w.x >> 16), bf2f(w.y & 0xffffu), bf2f(w.y >> 16)}; dist[u] = 16353 - 16 * kc; valid[u] = true; }
.LBB0_1499:
	s_and_b64 vcc, exec, s[66:67]
	s_cbranch_vccz .LBB0_1501
	v_ashrrev_i32_e32 v51, 31, v50
	s_waitcnt lgkmcnt(0)
	v_lshlrev_b64 v[14:15], 7, v[50:51]
	v_lshl_add_u64 v[14:15], v[78:79], 0, v[14:15]
	global_load_dwordx2 v[46:47], v[14:15], off
	v_lshlrev_b32_e32 v8, 4, v50
	s_andn2_b64 s[28:29], s[20:21], exec
	s_and_b64 s[20:21], s[20:21], exec
	v_sub_u32_e32 v8, 0x3fe1, v8
	s_or_b64 s[20:21], s[28:29], s[20:21]
	s_andn2_b64 s[28:29], s[58:59], exec
	s_and_b64 s[58:59], s[58:59], exec
	s_or_b64 s[58:59], s[28:29], s[58:59]
	s_or_b64 s[4:5], s[4:5], exec
	v_mov_b64_e32 v[20:21], v[12:13]
	v_mov_b64_e32 v[18:19], v[10:11]
	v_mov_b64_e32 v[16:17], v[8:9]
	v_mov_b64_e32 v[14:15], v[6:7]

; DI void snsa_unit(const Args& a, LAS unsigned char* lds, int s, int g) {
;     ...
;             for (int u = 0; u < 8; ++u) { const int kk = k0 + 32 * u; const int kc = kk < nkeys ? kk : k0;
;                 if (br == 0) { const u32x2 w = *(const u32x2*)(kcb + (size_t)kc * 64 + 4 * c16); x[u] = (f32x4){bf2f(w.x & 0xffffu), bf2f(w.x >> 16), bf2f(w.y & 0xffffu), bf2f(w.y >> 16)}; dist[u] = 16353 - 16 * kc; valid[u] = true; }
.LBB0_1511:
	s_and_b64 vcc, exec, s[68:69]
	s_cbranch_vccz .LBB0_1513
	v_ashrrev_i32_e32 v55, 31, v54
	v_lshlrev_b64 v[6:7], 7, v[54:55]
	v_lshl_add_u64 v[6:7], v[78:79], 0, v[6:7]
	global_load_dwordx2 v[50:51], v[6:7], off
	s_andn2_b64 s[28:29], s[20:21], exec
	s_and_b64 s[20:21], s[20:21], exec
	s_or_b64 s[20:21], s[28:29], s[20:21]
	s_andn2_b64 s[28:29], s[58:59], exec
	s_and_b64 s[58:59], s[58:59], exec
	s_or_b64 s[58:59], s[28:29], s[58:59]
	s_andn2_b64 s[28:29], s[4:5], exec
	s_and_b64 s[4:5], s[4:5], exec
	s_or_b64 s[4:5], s[28:29], s[4:5]
	s_or_b64 s[66:67], s[66:67], exec
	v_lshlrev_b32_e32 v6, 4, v54
	v_sub_u32_e32 v17, 0x3fe1, v6
	s_waitcnt lgkmcnt(0)
	v_mov_b64_e32 v[6:7], v[14:15]
	v_mov_b64_e32 v[8:9], v[16:17]
	v_mov_b64_e32 v[10:11], v[18:19]
	v_mov_b64_e32 v[12:13], v[20:21]

; DI void snsa_unit(const Args& a, LAS unsigned char* lds, int s, int g) {
;     ...
;             for (int u = 0; u < 8; ++u) { const int kk = k0 + 32 * u; const int kc = kk < nkeys ? kk : k0;
;                 if (br == 0) { const u32x2 w = *(const u32x2*)(kcb + (size_t)kc * 64 + 4 * c16); x[u] = (f32x4){bf2f(w.x & 0xffffu), bf2f(w.x >> 16), bf2f(w.y & 0xffffu), bf2f(w.y >> 16)}; dist[u] = 16353 - 16 * kc; valid[u] = true; }
.LBB0_1523:
	s_and_b64 vcc, exec, s[70:71]
	s_cbranch_vccz .LBB0_1525
	v_ashrrev_i32_e32 v59, 31, v58
	s_waitcnt lgkmcnt(0)
	v_lshlrev_b64 v[14:15], 7, v[58:59]
	v_lshl_add_u64 v[14:15], v[78:79], 0, v[14:15]
	global_load_dwordx2 v[54:55], v[14:15], off
	s_andn2_b64 s[28:29], s[20:21], exec
	s_and_b64 s[20:21], s[20:21], exec
	s_or_b64 s[20:21], s[28:29], s[20:21]
	s_andn2_b64 s[28:29], s[58:59], exec
	s_and_b64 s[58:59], s[58:59], exec
	v_lshlrev_b32_e32 v10, 4, v58
	s_or_b64 s[58:59], s[28:29], s[58:59]
	s_andn2_b64 s[28:29], s[4:5], exec
	s_and_b64 s[4:5], s[4:5], exec
	v_sub_u32_e32 v10, 0x3fe1, v10
	s_or_b64 s[4:5], s[28:29], s[4:5]
	s_andn2_b64 s[28:29], s[66:67], exec
	s_and_b64 s[66:67], s[66:67], exec
	s_or_b64 s[66:67], s[28:29], s[66:67]
	s_or_b64 s[68:69], s[68:69], exec
	v_mov_b64_e32 v[20:21], v[12:13]
	v_mov_b64_e32 v[18:19], v[10:11]
	v_mov_b64_e32 v[16:17], v[8:9]
	v_mov_b64_e32 v[14:15], v[6:7]

; DI void snsa_unit(const Args& a, LAS unsigned char* lds, int s, int g) {
;     ...
;             for (int u = 0; u < 8; ++u) { const int kk = k0 + 32 * u; const int kc = kk < nkeys ? kk : k0;
;                 if (br == 0) { const u32x2 w = *(const u32x2*)(kcb + (size_t)kc * 64 + 4 * c16); x[u] = (f32x4){bf2f(w.x & 0xffffu), bf2f(w.x >> 16), bf2f(w.y & 0xffffu), bf2f(w.y >> 16)}; dist[u] = 16353 - 16 * kc; valid[u] = true; }
.LBB0_1535:
	s_and_b64 vcc, exec, s[78:79]
	s_cbranch_vccz .LBB0_1537
	v_ashrrev_i32_e32 v63, 31, v62
	v_lshlrev_b64 v[6:7], 7, v[62:63]
	v_lshl_add_u64 v[6:7], v[78:79], 0, v[6:7]
	global_load_dwordx2 v[58:59], v[6:7], off
	s_andn2_b64 s[28:29], s[20:21], exec
	s_and_b64 s[20:21], s[20:21], exec
	s_or_b64 s[20:21], s[28:29], s[20:21]
	s_andn2_b64 s[28:29], s[58:59], exec
	s_and_b64 s[58:59], s[58:59], exec
	s_or_b64 s[58:59], s[28:29], s[58:59]
	s_andn2_b64 s[28:29], s[4:5], exec
	s_and_b64 s[4:5], s[4:5], exec
	s_or_b64 s[4:5], s[28:29], s[4:5]
	s_andn2_b64 s[28:29], s[66:67], exec
	s_and_b64 s[66:67], s[66:67], exec
	s_or_b64 s[66:67], s[28:29], s[66:67]
	s_andn2_b64 s[28:29], s[68:69], exec
	s_and_b64 s[68:69], s[68:69], exec
	s_or_b64 s[68:69], s[28:29], s[68:69]
	s_or_b64 s[70:71], s[70:71], exec
	v_lshlrev_b32_e32 v6, 4, v62
	v_sub_u32_e32 v19, 0x3fe1, v6
	s_waitcnt lgkmcnt(0)
	v_mov_b64_e32 v[6:7], v[14:15]
	v_mov_b64_e32 v[8:9], v[16:17]
	v_mov_b64_e32 v[10:11], v[18:19]
	v_mov_b64_e32 v[12:13], v[20:21]

; DI void snsa_unit(const Args& a, LAS unsigned char* lds, int s, int g) {
;     ...
;             for (int u = 0; u < 8; ++u) { const int kk = k0 + 32 * u; const int kc = kk < nkeys ? kk : k0;
;                 if (br == 0) { const u32x2 w = *(const u32x2*)(kcb + (size_t)kc * 64 + 4 * c16); x[u] = (f32x4){bf2f(w.x & 0xffffu), bf2f(w.x >> 16), bf2f(w.y & 0xffffu), bf2f(w.y >> 16)}; dist[u] = 16353 - 16 * kc; valid[u] = true; }
.LBB0_1547:
	s_and_b64 vcc, exec, s[82:83]
	s_cbranch_vccz .LBB0_1549
	v_ashrrev_i32_e32 v67, 31, v66
	s_waitcnt lgkmcnt(0)
	v_lshlrev_b64 v[14:15], 7, v[66:67]
	v_lshl_add_u64 v[14:15], v[78:79], 0, v[14:15]
	global_load_dwordx2 v[62:63], v[14:15], off
	s_andn2_b64 s[28:29], s[20:21], exec
	s_and_b64 s[20:21], s[20:21], exec
	s_or_b64 s[20:21], s[28:29], s[20:21]
	s_andn2_b64 s[28:29], s[58:59], exec
	s_and_b64 s[58:59], s[58:59], exec
	s_or_b64 s[58:59], s[28:29], s[58:59]
	s_andn2_b64 s[28:29], s[4:5], exec
	s_and_b64 s[4:5], s[4:5], exec
	v_lshlrev_b32_e32 v12, 4, v66
	s_or_b64 s[4:5], s[28:29], s[4:5]
	s_andn2_b64 s[28:29], s[66:67], exec
	s_and_b64 s[66:67], s[66:67], exec
	v_sub_u32_e32 v12, 0x3fe1, v12
	s_or_b64 s[66:67], s[28:29], s[66:67]
	s_andn2_b64 s[28:29], s[68:69], exec
	s_and_b64 s[68:69], s[68:69], exec
	s_or_b64 s[68:69], s[28:29], s[68:69]
	s_andn2_b64 s[28:29], s[70:71], exec
	s_and_b64 s[70:71], s[70:71], exec
	s_or_b64 s[70:71], s[28:29], s[70:71]
	s_or_b64 s[78:79], s[78:79], exec
	v_mov_b64_e32 v[20:21], v[12:13]
	v_mov_b64_e32 v[18:19], v[10:11]
	v_mov_b64_e32 v[16:17], v[8:9]
	v_mov_b64_e32 v[14:15], v[6:7]

; DI int rel_bucket(int d) {
;     if (d < 16) return d < 0 ? 0 : d;
;     int b = 16;
;     b += (d >= 21) + (d >= 27) + (d >= 35) + (d >= 46) + (d >= 59) + (d >= 77) + (d >= 99) + (d >= 128) + (d >= 166) + (d >= 216) + (d >= 280) + (d >= 363) + (d >= 470) + (d >= 609) + (d >= 790);
;     return b;
; }
; DI void snsa_unit(const Args& a, LAS unsigned char* lds, int s, int g) {
;     ...
;                 if (br == 0) { const u32x2 w = *(const u32x2*)(kcb + (size_t)kc * 64 + 4 * c16); x[u] = (f32x4){bf2f(w.x & 0xffffu), bf2f(w.x >> 16), bf2f(w.y & 0xffffu), bf2f(w.y >> 16)}; dist[u] = 16353 - 16 * kc; valid[u] = true; }
;                 else { const float* kp; const float* vp; snsa_key(a, br, kc, s, g, SEL, pt, kp, vp, dist[u], valid[u]); x[u] = *(const f32x4*)(kp + 4 * c16); if (c16 == 0 && kk < nkeys) VP[kk] = (unsigned long long)(uintptr_t)vp; } }
; #pragma unroll
;             for (int u = 0; u < 8; ++u) { const int kk = k0 + 32 * u;
;                 float p0 = x[u].x * q4[0].x + x[u].y * q4[0].y + x[u].z * q4[0].z + x[u].w * q4[0].w, p1 = x[u].x * q4[1].x + x[u].y * q4[1].y + x[u].z * q4[1].z + x[u].w * q4[1].w;
;                 float p2 = x[u].x * q4[2].x + x[u].y * q4[2].y + x[u].z * q4[2].z + x[u].w * q4[2].w, p3 = x[u].x * q4[3].x + x[u].y * q4[3].y + x[u].z * q4[3].z + x[u].w * q4[3].w;
;                 const bool o1 = (c16 & 1) != 0, o2 = (c16 & 2) != 0;
;                 float ka = o1 ? p2 : p0, kb2 = o1 ? p3 : p1; const float sa = o1 ? p0 : p2, sb = o1 ? p1 : p3;
;                 ka += __shfl_xor(sa, 1); kb2 += __shfl_xor(sb, 1);
;                 float e = o2 ? kb2 : ka; const float f = o2 ? ka : kb2;
;                 e += __shfl_xor(f, 2); e += __shfl_xor(e, 4); e += __shfl_xor(e, 8);
;                 if (c16 < 4 && kk < nkeys) SC[myh * 1024 + kk] = valid[u] ? e + rbias[rel_bucket(dist[u]) * 8 + g * 4 + myh] * LOG2E : -INFINITY; }
.LBB0_1559:
	s_and_b64 vcc, exec, s[82:83]
	s_cbranch_vccz .LBB0_1561
	v_ashrrev_i32_e32 v93, 31, v92
	v_lshlrev_b64 v[6:7], 7, v[92:93]
	v_lshl_add_u64 v[6:7], v[78:79], 0, v[6:7]
	global_load_dwordx2 v[66:67], v[6:7], off
	s_andn2_b64 s[24:25], s[20:21], exec
	s_and_b64 s[20:21], s[20:21], exec
	s_or_b64 s[20:21], s[24:25], s[20:21]
	s_andn2_b64 s[24:25], s[58:59], exec
	s_and_b64 s[28:29], s[58:59], exec
	s_or_b64 s[58:59], s[24:25], s[28:29]
	s_andn2_b64 s[24:25], s[4:5], exec
	s_and_b64 s[4:5], s[4:5], exec
	s_or_b64 s[4:5], s[24:25], s[4:5]
	s_andn2_b64 s[24:25], s[66:67], exec
	s_and_b64 s[28:29], s[66:67], exec
	s_or_b64 s[66:67], s[24:25], s[28:29]
	s_andn2_b64 s[24:25], s[68:69], exec
	s_and_b64 s[28:29], s[68:69], exec
	s_or_b64 s[68:69], s[24:25], s[28:29]
	s_andn2_b64 s[24:25], s[70:71], exec
	s_and_b64 s[28:29], s[70:71], exec
	s_or_b64 s[70:71], s[24:25], s[28:29]
	s_andn2_b64 s[24:25], s[78:79], exec
	s_and_b64 s[28:29], s[78:79], exec
	s_or_b64 s[78:79], s[24:25], s[28:29]
	s_or_b64 s[26:27], s[26:27], exec
	v_lshlrev_b32_e32 v6, 4, v92
	v_sub_u32_e32 v21, 0x3fe1, v6
	s_waitcnt lgkmcnt(0)
	v_mov_b64_e32 v[6:7], v[14:15]
	v_mov_b64_e32 v[8:9], v[16:17]
	v_mov_b64_e32 v[10:11], v[18:19]
	v_mov_b64_e32 v[12:13], v[20:21]
.LBB0_1561:
	s_waitcnt vmcnt(0) lgkmcnt(3)
	s_and_b64 vcc, exec, s[8:9]
	s_cbranch_vccnz .Lsnsa_sc_f32
	v_and_b32_e32 v41, 0xffff0000, v39
	v_lshlrev_b32_e32 v40, 16, v39
	v_and_b32_e32 v39, 0xffff0000, v38
	v_lshlrev_b32_e32 v38, 16, v38
	v_and_b32_e32 v45, 0xffff0000, v43
	v_lshlrev_b32_e32 v44, 16, v43
	v_and_b32_e32 v43, 0xffff0000, v42
	v_lshlrev_b32_e32 v42, 16, v42
	v_and_b32_e32 v49, 0xffff0000, v47
	v_lshlrev_b32_e32 v48, 16, v47
	v_and_b32_e32 v47, 0xffff0000, v46
	v_lshlrev_b32_e32 v46, 16, v46
	v_and_b32_e32 v53, 0xffff0000, v51
	v_lshlrev_b32_e32 v52, 16, v51
	v_and_b32_e32 v51, 0xffff0000, v50
	v_lshlrev_b32_e32 v50, 16, v50
	v_and_b32_e32 v57, 0xffff0000, v55
	v_lshlrev_b32_e32 v56, 16, v55
	v_and_b32_e32 v55, 0xffff0000, v54
	v_lshlrev_b32_e32 v54, 16, v54
	v_and_b32_e32 v61, 0xffff0000, v59
	v_lshlrev_b32_e32 v60, 16, v59
	v_and_b32_e32 v59, 0xffff0000, v58
	v_lshlrev_b32_e32 v58, 16, v58
	v_and_b32_e32 v65, 0xffff0000, v63
	v_lshlrev_b32_e32 v64, 16, v63
	v_and_b32_e32 v63, 0xffff0000, v62
	v_lshlrev_b32_e32 v62, 16, v62
	v_and_b32_e32 v69, 0xffff0000, v67
	v_lshlrev_b32_e32 v68, 16, v67
	v_and_b32_e32 v67, 0xffff0000, v66
	v_lshlrev_b32_e32 v66, 16, v66
.Lsnsa_sc_f32:
	v_mul_f32_e32 v14, v23, v39
	s_waitcnt lgkmcnt(0)
	v_mul_f32_e32 v15, v27, v39
	s_waitcnt lgkmcnt(1)
	v_mul_f32_e32 v16, v31, v39
	s_waitcnt lgkmcnt(0)
	v_mul_f32_e32 v17, v35, v39
	v_fmac_f32_e32 v14, v22, v38
	v_fmac_f32_e32 v15, v26, v38
	v_fmac_f32_e32 v16, v30, v38
	v_fmac_f32_e32 v17, v34, v38
	v_fmac_f32_e32 v14, v24, v40
	v_fmac_f32_e32 v15, v28, v40
	v_fmac_f32_e32 v16, v32, v40
	v_fmac_f32_e32 v17, v36, v40
	v_fmac_f32_e32 v14, v25, v41
	v_fmac_f32_e32 v15, v29, v41
	v_fmac_f32_e32 v16, v33, v41
	v_fmac_f32_e32 v17, v37, v41
	v_cndmask_b32_e64 v18, v14, v16, s[10:11]
	v_cndmask_b32_e64 v19, v15, v17, s[10:11]
	ds_bpermute_b32 v18, v5, v18
	ds_bpermute_b32 v19, v5, v19
	v_cndmask_b32_e64 v14, v16, v14, s[10:11]
	v_cndmask_b32_e64 v15, v17, v15, s[10:11]
	s_waitcnt lgkmcnt(1)
	v_add_f32_e32 v14, v14, v18
	s_waitcnt lgkmcnt(0)
	v_add_f32_e32 v15, v15, v19
	v_cndmask_b32_e64 v16, v14, v15, s[12:13]
	ds_bpermute_b32 v16, v118, v16
	v_cndmask_b32_e64 v14, v15, v14, s[12:13]
	s_waitcnt lgkmcnt(0)
	v_add_f32_e32 v14, v14, v16
	ds_bpermute_b32 v15, v119, v14
	s_waitcnt lgkmcnt(0)
	v_add_f32_e32 v14, v14, v15
	ds_bpermute_b32 v15, v120, v14
	s_and_saveexec_b64 s[24:25], s[14:15]
	s_cbranch_execz .LBB0_1569
	v_mov_b32_e32 v16, 0xff800000
	s_and_saveexec_b64 s[28:29], s[20:21]
	s_cbranch_execz .LBB0_1568
	v_cmp_lt_i32_e32 vcc, 15, v6
	s_and_saveexec_b64 s[82:83], vcc
	s_xor_b64 s[82:83], exec, s[82:83]
	s_cbranch_execz .LBB0_1565
	v_cmp_lt_u32_e32 vcc, 20, v6
	s_nop 1
	v_cndmask_b32_e64 v16, 0, 1, vcc
	v_cmp_lt_u32_e32 vcc, 45, v6
	s_nop 1
	v_cndmask_b32_e64 v17, 0, 1, vcc
	v_cmp_lt_u32_e32 vcc, s86, v6
	s_nop 1
	v_cndmask_b32_e64 v18, 0, 1, vcc
	v_cmp_lt_u32_e32 vcc, s88, v6
	s_nop 1
	v_cndmask_b32_e64 v19, 0, 1, vcc
	v_cmp_lt_u32_e32 vcc, s90, v6
	s_nop 1
	v_cndmask_b32_e64 v20, 0, 1, vcc
	v_cmp_lt_u32_e32 vcc, s92, v6
	s_nop 1
	v_cndmask_b32_e64 v21, 0, 1, vcc
	v_cmp_lt_u32_e32 vcc, s94, v6
	s_nop 1
	v_cndmask_b32_e64 v38, 0, 1, vcc
	v_cmp_lt_u32_e32 vcc, 26, v6
	s_nop 1
	v_cndmask_b32_e64 v39, 16, 17, vcc
	v_cmp_lt_u32_e32 vcc, 34, v6
	s_nop 1
	v_addc_co_u32_e32 v16, vcc, v39, v16, vcc
	v_cmp_lt_u32_e32 vcc, 58, v6
	s_nop 1
	v_addc_co_u32_e32 v16, vcc, v16, v17, vcc
	v_cmp_lt_u32_e32 vcc, s87, v6
	s_nop 1
	v_addc_co_u32_e32 v16, vcc, v16, v18, vcc
	v_cmp_lt_u32_e32 vcc, s89, v6
	s_nop 1
	v_addc_co_u32_e32 v16, vcc, v16, v19, vcc
	v_cmp_lt_u32_e32 vcc, s91, v6
	s_nop 1
	v_addc_co_u32_e32 v16, vcc, v16, v20, vcc
	v_cmp_lt_u32_e32 vcc, s93, v6
	s_nop 1
	v_addc_co_u32_e32 v16, vcc, v16, v21, vcc
	v_cmp_lt_u32_e32 vcc, s95, v6
	s_nop 1
	v_addc_co_u32_e32 v17, vcc, v16, v38, vcc

; DI void snsa_unit(const Args& a, LAS unsigned char* lds, int s, int g) {
;     ...
;               for (int u = 0; u < 8; ++u) { const int kk = k0 + 32 * u; const int kc = kk < nkeys ? kk : k0;
;                   if (br == 0) { const u32x2 w = *(const u32x2*)(vcb + (size_t)kc * 64 + 4 * c16); v[u] = (f32x4){bf2f(w.x & 0xffffu), bf2f(w.x >> 16), bf2f(w.y & 0xffffu), bf2f(w.y >> 16)}; }
;                   else v[u] = *(const f32x4*)((const float*)(uintptr_t)VP[kc] + 4 * c16); }
.LBB0_1654:
	s_andn2_b64 vcc, exec, s[18:19]
	s_cbranch_vccnz .LBB0_1656
	global_load_dwordx2 v[62:63], v[66:67], off

; DI void snsa_unit(const Args& a, LAS unsigned char* lds, int s, int g) {
;     ...
;               for (int u = 0; u < 8; ++u) { const int kk = k0 + 32 * u; const int kc = kk < nkeys ? kk : k0;
;                   if (br == 0) { const u32x2 w = *(const u32x2*)(vcb + (size_t)kc * 64 + 4 * c16); v[u] = (f32x4){bf2f(w.x & 0xffffu), bf2f(w.x >> 16), bf2f(w.y & 0xffffu), bf2f(w.y >> 16)}; }
;                   else v[u] = *(const f32x4*)((const float*)(uintptr_t)VP[kc] + 4 * c16); }
.LBB0_1658:
	s_andn2_b64 vcc, exec, s[18:19]
	s_cbranch_vccnz .LBB0_1660
	v_ashrrev_i32_e32 v19, 31, v18
	v_lshlrev_b64 v[18:19], 7, v[18:19]
	v_lshl_add_u64 v[18:19], v[80:81], 0, v[18:19]
	global_load_dwordx2 v[58:59], v[18:19], off

; DI void snsa_unit(const Args& a, LAS unsigned char* lds, int s, int g) {
;     ...
;               for (int u = 0; u < 8; ++u) { const int kk = k0 + 32 * u; const int kc = kk < nkeys ? kk : k0;
;                   if (br == 0) { const u32x2 w = *(const u32x2*)(vcb + (size_t)kc * 64 + 4 * c16); v[u] = (f32x4){bf2f(w.x & 0xffffu), bf2f(w.x >> 16), bf2f(w.y & 0xffffu), bf2f(w.y >> 16)}; }
;                   else v[u] = *(const f32x4*)((const float*)(uintptr_t)VP[kc] + 4 * c16); }
.LBB0_1662:
	s_andn2_b64 vcc, exec, s[18:19]
	s_cbranch_vccnz .LBB0_1664
	v_ashrrev_i32_e32 v19, 31, v18
	v_lshlrev_b64 v[18:19], 7, v[18:19]
	v_lshl_add_u64 v[18:19], v[80:81], 0, v[18:19]
	global_load_dwordx2 v[54:55], v[18:19], off

; DI void snsa_unit(const Args& a, LAS unsigned char* lds, int s, int g) {
;     ...
;               for (int u = 0; u < 8; ++u) { const int kk = k0 + 32 * u; const int kc = kk < nkeys ? kk : k0;
;                   if (br == 0) { const u32x2 w = *(const u32x2*)(vcb + (size_t)kc * 64 + 4 * c16); v[u] = (f32x4){bf2f(w.x & 0xffffu), bf2f(w.x >> 16), bf2f(w.y & 0xffffu), bf2f(w.y >> 16)}; }
;                   else v[u] = *(const f32x4*)((const float*)(uintptr_t)VP[kc] + 4 * c16); }
.LBB0_1666:
	s_andn2_b64 vcc, exec, s[18:19]
	s_cbranch_vccnz .LBB0_1668
	v_ashrrev_i32_e32 v19, 31, v18
	v_lshlrev_b64 v[18:19], 7, v[18:19]
	v_lshl_add_u64 v[18:19], v[80:81], 0, v[18:19]
	global_load_dwordx2 v[50:51], v[18:19], off

; DI void snsa_unit(const Args& a, LAS unsigned char* lds, int s, int g) {
;     ...
;               for (int u = 0; u < 8; ++u) { const int kk = k0 + 32 * u; const int kc = kk < nkeys ? kk : k0;
;                   if (br == 0) { const u32x2 w = *(const u32x2*)(vcb + (size_t)kc * 64 + 4 * c16); v[u] = (f32x4){bf2f(w.x & 0xffffu), bf2f(w.x >> 16), bf2f(w.y & 0xffffu), bf2f(w.y >> 16)}; }
;                   else v[u] = *(const f32x4*)((const float*)(uintptr_t)VP[kc] + 4 * c16); }
.LBB0_1670:
	s_andn2_b64 vcc, exec, s[18:19]
	s_cbranch_vccnz .LBB0_1672
	v_ashrrev_i32_e32 v19, 31, v18
	v_lshlrev_b64 v[18:19], 7, v[18:19]
	v_lshl_add_u64 v[18:19], v[80:81], 0, v[18:19]
	global_load_dwordx2 v[46:47], v[18:19], off

; DI void snsa_unit(const Args& a, LAS unsigned char* lds, int s, int g) {
;     ...
;               for (int u = 0; u < 8; ++u) { const int kk = k0 + 32 * u; const int kc = kk < nkeys ? kk : k0;
;                   if (br == 0) { const u32x2 w = *(const u32x2*)(vcb + (size_t)kc * 64 + 4 * c16); v[u] = (f32x4){bf2f(w.x & 0xffffu), bf2f(w.x >> 16), bf2f(w.y & 0xffffu), bf2f(w.y >> 16)}; }
;                   else v[u] = *(const f32x4*)((const float*)(uintptr_t)VP[kc] + 4 * c16); }
.LBB0_1674:
	s_andn2_b64 vcc, exec, s[18:19]
	s_cbranch_vccnz .LBB0_1676
	v_ashrrev_i32_e32 v19, 31, v18
	v_lshlrev_b64 v[18:19], 7, v[18:19]
	v_lshl_add_u64 v[18:19], v[80:81], 0, v[18:19]
	global_load_dwordx2 v[42:43], v[18:19], off

; DI void snsa_unit(const Args& a, LAS unsigned char* lds, int s, int g) {
;     ...
;               for (int u = 0; u < 8; ++u) { const int kk = k0 + 32 * u; const int kc = kk < nkeys ? kk : k0;
;                   if (br == 0) { const u32x2 w = *(const u32x2*)(vcb + (size_t)kc * 64 + 4 * c16); v[u] = (f32x4){bf2f(w.x & 0xffffu), bf2f(w.x >> 16), bf2f(w.y & 0xffffu), bf2f(w.y >> 16)}; }
;                   else v[u] = *(const f32x4*)((const float*)(uintptr_t)VP[kc] + 4 * c16); }
.LBB0_1678:
	s_andn2_b64 vcc, exec, s[18:19]
	s_cbranch_vccnz .LBB0_1680
	v_ashrrev_i32_e32 v19, 31, v18
	v_lshlrev_b64 v[18:19], 7, v[18:19]
	v_lshl_add_u64 v[18:19], v[80:81], 0, v[18:19]
	global_load_dwordx2 v[38:39], v[18:19], off

; DI void snsa_unit(const Args& a, LAS unsigned char* lds, int s, int g) {
;     ...
;               for (int u = 0; u < 8; ++u) { const int kk = k0 + 32 * u; const int kc = kk < nkeys ? kk : k0;
;                   if (br == 0) { const u32x2 w = *(const u32x2*)(vcb + (size_t)kc * 64 + 4 * c16); v[u] = (f32x4){bf2f(w.x & 0xffffu), bf2f(w.x >> 16), bf2f(w.y & 0xffffu), bf2f(w.y >> 16)}; }
;                   else v[u] = *(const f32x4*)((const float*)(uintptr_t)VP[kc] + 4 * c16); }
; #pragma unroll
;               for (int u = 0; u < 8; ++u) { const int kk = k0 + 32 * u; if (kk < nkeys) {
; #pragma unroll
;                   for (int hq = 0; hq < 4; ++hq) o[hq] = o[hq] + v[u] * SC[hq * 1024 + kk]; } }
.LBB0_1684:
	ds_read2st64_b32 v[68:69], v88 offset1:16
	s_waitcnt vmcnt(0) lgkmcnt(0)
	s_and_b64 vcc, exec, s[8:9]
	s_cbranch_vccnz .Lsnsa_pv_f32
	v_and_b32_e32 v65, 0xffff0000, v63
	v_lshlrev_b32_e32 v64, 16, v63
	v_and_b32_e32 v63, 0xffff0000, v62
	v_lshlrev_b32_e32 v62, 16, v62
	v_and_b32_e32 v61, 0xffff0000, v59
	v_lshlrev_b32_e32 v60, 16, v59
	v_and_b32_e32 v59, 0xffff0000, v58
	v_lshlrev_b32_e32 v58, 16, v58
	v_and_b32_e32 v57, 0xffff0000, v55
	v_lshlrev_b32_e32 v56, 16, v55
	v_and_b32_e32 v55, 0xffff0000, v54
	v_lshlrev_b32_e32 v54, 16, v54
	v_and_b32_e32 v53, 0xffff0000, v51
	v_lshlrev_b32_e32 v52, 16, v51
	v_and_b32_e32 v51, 0xffff0000, v50
	v_lshlrev_b32_e32 v50, 16, v50
	v_and_b32_e32 v49, 0xffff0000, v47
	v_lshlrev_b32_e32 v48, 16, v47
	v_and_b32_e32 v47, 0xffff0000, v46
	v_lshlrev_b32_e32 v46, 16, v46
	v_and_b32_e32 v45, 0xffff0000, v43
	v_lshlrev_b32_e32 v44, 16, v43
	v_and_b32_e32 v43, 0xffff0000, v42
	v_lshlrev_b32_e32 v42, 16, v42
	v_and_b32_e32 v41, 0xffff0000, v39
	v_lshlrev_b32_e32 v40, 16, v39
	v_and_b32_e32 v39, 0xffff0000, v38
	v_lshlrev_b32_e32 v38, 16, v38
	v_lshlrev_b32_e32 v18, 16, v20
	v_and_b32_e32 v19, 0xffff0000, v20
	v_lshlrev_b32_e32 v20, 16, v21
	v_and_b32_e32 v21, 0xffff0000, v21
.Lsnsa_pv_f32:
	v_pk_fma_f32 v[12:13], v[68:69], v[64:65], v[12:13] op_sel_hi:[0,1,1]
	v_pk_fma_f32 v[10:11], v[68:69], v[62:63], v[10:11] op_sel_hi:[0,1,1]
	v_mov_b32_e32 v68, v69
	v_pk_fma_f32 v[16:17], v[68:69], v[64:65], v[16:17] op_sel_hi:[0,1,1]
	v_pk_fma_f32 v[14:15], v[68:69], v[62:63], v[14:15] op_sel_hi:[0,1,1]
	ds_read2st64_b32 v[68:69], v88 offset0:32 offset1:48
	s_waitcnt lgkmcnt(0)
	v_pk_fma_f32 v[8:9], v[68:69], v[64:65], v[8:9] op_sel_hi:[0,1,1]
	v_pk_fma_f32 v[6:7], v[68:69], v[62:63], v[6:7] op_sel_hi:[0,1,1]
	v_mov_b32_e32 v68, v69
	v_pk_fma_f32 v[4:5], v[68:69], v[64:65], v[4:5] op_sel_hi:[0,1,1]
	v_pk_fma_f32 v[2:3], v[68:69], v[62:63], v[2:3] op_sel_hi:[0,1,1]
	v_add_u32_e32 v62, 0x80, v88
	s_and_saveexec_b64 s[18:19], s[36:37]
	s_cbranch_execz .LBB0_1691
	ds_read2st64_b32 v[64:65], v62 offset1:16
	s_waitcnt lgkmcnt(0)
	v_pk_fma_f32 v[12:13], v[64:65], v[60:61], v[12:13] op_sel_hi:[0,1,1]
	v_pk_fma_f32 v[10:11], v[64:65], v[58:59], v[10:11] op_sel_hi:[0,1,1]
	v_mov_b32_e32 v64, v65
	v_pk_fma_f32 v[16:17], v[64:65], v[60:61], v[16:17] op_sel_hi:[0,1,1]
	v_pk_fma_f32 v[14:15], v[64:65], v[58:59], v[14:15] op_sel_hi:[0,1,1]
	ds_read2st64_b32 v[64:65], v62 offset0:32 offset1:48
	s_waitcnt lgkmcnt(0)
	v_pk_fma_f32 v[8:9], v[64:65], v[60:61], v[8:9] op_sel_hi:[0,1,1]
	v_pk_fma_f32 v[6:7], v[64:65], v[58:59], v[6:7] op_sel_hi:[0,1,1]
	v_mov_b32_e32 v64, v65
	v_pk_fma_f32 v[4:5], v[64:65], v[60:61], v[4:5] op_sel_hi:[0,1,1]
	v_pk_fma_f32 v[2:3], v[64:65], v[58:59], v[2:3] op_sel_hi:[0,1,1]
	s_or_b64 exec, exec, s[18:19]
	s_and_saveexec_b64 s[18:19], s[34:35]
	s_cbranch_execnz .LBB0_1692
